# attention: K half-tile staging, V 3-deep LDS ring, one barrier per tile (plus earlier changes)
# speedup vs baseline: 1.0332x; 1.0216x over previous
.LBB0_336:
	v_mov_b32_e32 v52, v162
	v_mov_b32_e32 v123, v99
	v_ashrrev_i32_e32 v50, 4, v52
	v_lshlrev_b32_e32 v20, 3, v52
	v_add_u32_e32 v21, 32, v50
	v_and_b32_e32 v24, 0x78, v20
	v_mad_i64_i32 v[2:3], s[12:13], v50, s52, 0
	v_mad_i64_i32 v[4:5], s[12:13], v21, s52, 0
	v_or_b32_e32 v2, v2, v24
	v_or_b32_e32 v4, v4, v24
	v_lshlrev_b64 v[10:11], 1, v[2:3]
	v_lshlrev_b64 v[12:13], 1, v[4:5]
	v_lshl_add_u64 v[2:3], s[36:37], 0, v[10:11]
	v_lshl_add_u64 v[6:7], s[36:37], 0, v[12:13]
	v_lshl_add_u64 v[10:11], s[34:35], 0, v[10:11]
	v_lshl_add_u64 v[14:15], s[34:35], 0, v[12:13]
	global_load_dwordx4 v[2:5], v[2:3], off
	s_nop 0
	global_load_dwordx4 v[6:9], v[6:7], off
	s_nop 0
	global_load_dwordx4 v[10:13], v[10:11], off
	s_nop 0
	global_load_dwordx4 v[14:17], v[14:15], off
	s_lshl_b32 s12, s8, 7
	s_add_u32 s8, s76, s12
	s_addc_u32 s9, s77, 0
	v_ashrrev_i32_e32 v26, 1, v52
	v_bfe_u32 v51, v52, 5, 1
	v_bfi_b32 v23, s18, v26, v52
	v_mov_b64_e32 v[18:19], s[8:9]
	v_bfe_u32 v27, v20, 5, 2
	v_lshlrev_b32_e32 v28, 5, v50
	v_and_b32_e32 v20, 24, v20
	v_add_u32_e32 v30, 64, v50
	v_lshrrev_b32_e32 v22, 5, v52
	v_lshlrev_b32_e32 v98, 4, v51
	v_add_u32_e32 v31, 0x60, v50
	v_mad_i64_i32 v[18:19], s[8:9], v23, s49, v[18:19]
	v_and_or_b32 v28, v28, s51, v20
	v_lshrrev_b32_e32 v33, 1, v21
	v_lshlrev_b32_e32 v35, 8, v21
	v_mad_i64_i32 v[20:21], s[8:9], v30, s52, 0
	v_and_or_b32 v32, v22, s50, v27
	v_mad_i64_i32 v[22:23], s[8:9], v31, s52, 0
	v_lshl_add_u64 v[18:19], v[18:19], 0, v[98:99]
	v_lshlrev_b32_e32 v28, 1, v28
	v_or_b32_e32 v20, v20, v24
	v_and_b32_e32 v25, 0x70, v52
	v_lshlrev_b32_e32 v29, 8, v50
	v_lshlrev_b32_e32 v34, 1, v24
	v_and_or_b32 v27, v33, s50, v27
	v_or_b32_e32 v22, v22, v24
	global_load_dwordx4 v[118:121], v[18:19], off
	global_load_dwordx4 v[114:117], v[18:19], off offset:32
	global_load_dwordx4 v[110:113], v[18:19], off offset:64
	global_load_dwordx4 v[106:109], v[18:19], off offset:96
	v_lshl_or_b32 v24, v32, 9, v28
	v_lshlrev_b64 v[18:19], 1, v[20:21]
	v_bitop3_b32 v29, v34, v29, v25 bitop3:0xde
	v_bitop3_b32 v25, v34, v35, v25 bitop3:0xde
	v_lshl_or_b32 v27, v27, 9, v28
	v_lshlrev_b64 v[20:21], 1, v[22:23]
	v_add_u32_e32 v183, 0, v24
	v_lshl_add_u64 v[22:23], s[36:37], 0, v[18:19]
	v_add_u32_e32 v181, 0, v29
	v_add_u32_e32 v182, 0, v25
	v_add_u32_e32 v184, 0, v27
	v_lshl_add_u64 v[24:25], s[36:37], 0, v[20:21]
	v_lshl_add_u64 v[18:19], s[34:35], 0, v[18:19]
	v_lshl_add_u64 v[20:21], s[34:35], 0, v[20:21]
	s_waitcnt vmcnt(0)
	v_and_b32_e32 v55, 63, v52
	v_and_b32_e32 v54, 0xffffffe0, v26
	v_and_b32_e32 v53, 31, v52
	v_add_u32_e32 v185, s75, v54
	v_cmp_gt_u32_e32 vcc, 32, v55
	v_or_b32_e32 v178, v185, v53
	v_mov_b32_e32 v124, v99
	v_cndmask_b32_e32 v122, 0, v170, vcc
	v_mov_b32_e32 v125, v99
	s_barrier
	s_waitcnt vmcnt(7)
	ds_write_b128 v183, v[2:5]
	s_waitcnt vmcnt(6)
	ds_write_b128 v184, v[6:9]
	s_waitcnt vmcnt(5)
	ds_write_b128 v181, v[10:13] offset:32768
	s_waitcnt vmcnt(4)
	ds_write_b128 v182, v[14:17] offset:32768
	s_waitcnt lgkmcnt(0)
	s_barrier
	global_load_dwordx4 v[34:37], v[22:23], off
	global_load_dwordx4 v[38:41], v[24:25], off
	global_load_dwordx4 v[42:45], v[18:19], off
	global_load_dwordx4 v[46:49], v[20:21], off
	ds_read_b32 v2, v173
	ds_read_b32 v3, v171
	s_waitcnt lgkmcnt(1)
	v_readfirstlane_b32 s43, v2
	s_waitcnt lgkmcnt(0)
	v_readfirstlane_b32 s42, v3
	v_lshlrev_b32_e32 v18, 4, v52
	v_mfma_f32_32x32x16_bf16 v[2:17], v[122:125], v[102:105], 0
	v_lshlrev_b32_e32 v64, 8, v53
	v_and_b32_e32 v65, 0x70, v18
	s_add_i32 s8, s12, 0
	v_bitop3_b32 v18, v98, v64, v65 bitop3:0xde
	v_add_u32_e32 v186, s8, v18
	ds_read_b128 v[56:59], v186 offset:32768
	ds_read_b128 v[60:63], v186 offset:40960
	v_lshlrev_b32_e32 v179, 2, v51
	s_waitcnt vmcnt(7) lgkmcnt(1)
	v_mfma_f32_32x32x16_bf16 v[18:33], v[56:59], v[118:121], v[2:17]
	v_or_b32_e32 v56, 32, v98
	v_bitop3_b32 v56, v56, v64, v65 bitop3:0xde
	v_add_u32_e32 v187, s8, v56
	s_waitcnt lgkmcnt(0)
	v_mfma_f32_32x32x16_bf16 v[2:17], v[60:63], v[118:121], v[2:17]
	ds_read_b128 v[56:59], v187 offset:32768
	ds_read_b128 v[60:63], v187 offset:40960
	s_waitcnt vmcnt(6) lgkmcnt(1)
	v_mfma_f32_32x32x16_bf16 v[18:33], v[56:59], v[114:117], v[18:33]
	v_or_b32_e32 v56, 64, v98
	v_bitop3_b32 v56, v56, v64, v65 bitop3:0xde
	v_add_u32_e32 v188, s8, v56
	s_waitcnt lgkmcnt(0)
	v_mfma_f32_32x32x16_bf16 v[2:17], v[60:63], v[114:117], v[2:17]
	ds_read_b128 v[56:59], v188 offset:32768
	ds_read_b128 v[60:63], v188 offset:40960
	s_waitcnt vmcnt(5) lgkmcnt(1)
	v_mfma_f32_32x32x16_bf16 v[18:33], v[56:59], v[110:113], v[18:33]
	v_or_b32_e32 v56, 0x60, v98
	v_bitop3_b32 v56, v56, v64, v65 bitop3:0xde
	v_add_u32_e32 v189, s8, v56
	s_waitcnt lgkmcnt(0)
	v_mfma_f32_32x32x16_bf16 v[2:17], v[60:63], v[110:113], v[2:17]
	ds_read_b128 v[56:59], v189 offset:32768
	ds_read_b128 v[60:63], v189 offset:40960
	s_waitcnt vmcnt(4) lgkmcnt(1)
	v_mfma_f32_32x32x16_bf16 v[18:33], v[56:59], v[106:109], v[18:33]
	v_add_u32_e32 v56, 0x9e, v185
	v_cmp_gt_u32_e64 s[8:9], s53, v56
	s_waitcnt lgkmcnt(0)
	v_mfma_f32_32x32x16_bf16 v[2:17], v[60:63], v[106:109], v[2:17]
	s_and_saveexec_b64 s[12:13], s[8:9]
	s_cbranch_execz .LBB0_338
	v_sub_u32_e32 v51, v179, v178
	v_lshl_add_u32 v51, v51, 2, s1
	ds_read2_b32 v[56:57], v51 offset0:240 offset1:241
	ds_read2_b32 v[58:59], v51 offset0:242 offset1:243
	ds_read2_b32 v[60:61], v51 offset0:248 offset1:249
	ds_read2_b32 v[62:63], v51 offset0:250 offset1:251
	ds_read2_b32 v[64:65], v51 offset0:224 offset1:225
	ds_read2_b32 v[66:67], v51 offset0:226 offset1:227
	ds_read2_b32 v[68:69], v51 offset0:232 offset1:233
	ds_read2_b32 v[70:71], v51 offset0:234 offset1:235
	s_waitcnt lgkmcnt(4)
	v_pk_add_f32 v[32:33], v[32:33], v[62:63]
	v_pk_add_f32 v[30:31], v[30:31], v[60:61]
	v_pk_add_f32 v[28:29], v[28:29], v[58:59]
	v_pk_add_f32 v[26:27], v[26:27], v[56:57]
	s_waitcnt lgkmcnt(0)
	v_pk_add_f32 v[24:25], v[24:25], v[70:71]
	v_pk_add_f32 v[22:23], v[22:23], v[68:69]
	v_pk_add_f32 v[20:21], v[20:21], v[66:67]
	v_pk_add_f32 v[18:19], v[18:19], v[64:65]
	v_add_u32_e32 v64, 0x400, v51
	v_add_u32_e32 v66, 0x408, v51
	v_add_u32_e32 v68, 0x420, v51
	v_add_u32_e32 v70, 0x428, v51
	v_add_u32_e32 v56, 0x440, v51
	v_add_u32_e32 v58, 0x448, v51
	v_add_u32_e32 v60, 0x460, v51
	v_add_u32_e32 v51, 0x468, v51
	ds_read2_b32 v[56:57], v56 offset1:1
	ds_read2_b32 v[58:59], v58 offset1:1
	ds_read2_b32 v[60:61], v60 offset1:1
	ds_read2_b32 v[62:63], v51 offset1:1
	ds_read2_b32 v[64:65], v64 offset1:1
	ds_read2_b32 v[66:67], v66 offset1:1
	ds_read2_b32 v[68:69], v68 offset1:1
	ds_read2_b32 v[70:71], v70 offset1:1
	s_waitcnt lgkmcnt(4)
	v_pk_add_f32 v[16:17], v[16:17], v[62:63]
	v_pk_add_f32 v[14:15], v[14:15], v[60:61]
	v_pk_add_f32 v[12:13], v[12:13], v[58:59]
	v_pk_add_f32 v[10:11], v[10:11], v[56:57]
	s_waitcnt lgkmcnt(0)
	v_pk_add_f32 v[8:9], v[8:9], v[70:71]
	v_pk_add_f32 v[6:7], v[6:7], v[68:69]
	v_pk_add_f32 v[4:5], v[4:5], v[66:67]
	v_pk_add_f32 v[2:3], v[2:3], v[64:65]
.LBB0_338:
	s_or_b64 exec, exec, s[12:13]
	v_mov_b32_e32 v51, s43
	v_mov_b32_e32 v56, s42
	v_cmp_gt_i32_e64 s[12:13], 0, v185
	s_nop 1
	v_max_f32_e32 v57, v18, v18
	v_mov_b32_e32 v190, 0
	v_cndmask_b32_e64 v51, v51, v56, s[12:13]
	v_cndmask_b32_e64 v56, v51, 0, s[8:9]
	v_max_f32_e32 v51, v19, v19
	v_max_f32_e32 v51, v57, v51
	v_max3_f32 v51, v51, v20, v21
	v_max3_f32 v51, v51, v22, v23
	v_max3_f32 v51, v51, v24, v25
	v_max3_f32 v51, v51, v26, v27
	v_max3_f32 v51, v51, v28, v29
	v_max3_f32 v51, v51, v30, v31
	v_max3_f32 v51, v51, v32, v33
	v_max3_f32 v51, v51, v2, v3
	v_max3_f32 v51, v51, v4, v5
	v_max3_f32 v51, v51, v6, v7
	v_max3_f32 v51, v51, v8, v9
	v_max3_f32 v51, v51, v10, v11
	v_max3_f32 v51, v51, v12, v13
	v_max3_f32 v51, v51, v14, v15
	v_max3_f32 v51, v51, v16, v17
	v_mov_b32_e32 v57, v51
	s_nop 1
	v_permlane32_swap_b32_e32 v51, v57
	v_max_f32_e32 v57, v57, v57
	v_max_f32_e32 v51, v51, v51
	v_max_f32_e32 v51, v51, v57
	v_add_f32_e32 v57, v56, v51
	v_sub_f32_e32 v191, s43, v57
	v_sub_f32_e32 v190, 0, v57
	v_sub_f32_e32 v192, s42, v57
	v_mov_b32_e32 v176, 0
	v_readfirstlane_b32 s98, v185
	s_mov_b32 s99, 64
	v_sub_f32_e32 v56, v56, v57
	v_add_f32_e32 v3, v3, v56
	v_add_f32_e32 v2, v2, v56
	v_add_f32_e32 v4, v4, v56
	v_exp_f32_e32 v196, v3
	v_lshlrev_b32_e32 v3, 4, v55
	s_xor_b64 s[42:43], s[2:3], -1
	v_exp_f32_e32 v195, v2
	v_exp_f32_e32 v197, v4
	v_lshlrev_b32_e32 v2, 3, v55
	v_and_b32_e32 v3, 0xc0, v3
	v_lshlrev_b32_e32 v4, 1, v55
	v_and_or_b32 v3, v2, 24, v3
	v_and_b32_e32 v4, 32, v4
	v_and_b32_e32 v2, 0x100, v2
	s_cmp_lg_u32 0, -1
	v_or3_b32 v2, v3, v4, v2
	s_cselect_b32 s2, 0, 0
	v_add_u32_e32 v180, s2, v2
	s_addk_i32 s2, 0x4000
	v_add_u32_e32 v177, s2, v2
	v_add_lshl_u32 v2, v185, v53, 2
	v_ashrrev_i32_e32 v51, 31, v50
	v_add_f32_e32 v18, v18, v56
	v_add_f32_e32 v19, v19, v56
	v_add_f32_e32 v20, v20, v56
	v_add_f32_e32 v21, v21, v56
	v_add_f32_e32 v22, v22, v56
	v_add_f32_e32 v23, v23, v56
	v_add_f32_e32 v24, v24, v56
	v_add_f32_e32 v25, v25, v56
	v_add_f32_e32 v26, v26, v56
	v_add_f32_e32 v27, v27, v56
	v_add_f32_e32 v28, v28, v56
	v_add_f32_e32 v29, v29, v56
	v_add_f32_e32 v30, v30, v56
	v_add_f32_e32 v31, v31, v56
	v_add_f32_e32 v32, v32, v56
	v_add_f32_e32 v33, v33, v56
	v_add_f32_e32 v5, v5, v56
	v_add_f32_e32 v6, v6, v56
	v_add_f32_e32 v7, v7, v56
	v_add_f32_e32 v8, v8, v56
	v_add_f32_e32 v9, v9, v56
	v_add_f32_e32 v10, v10, v56
	v_add_f32_e32 v11, v11, v56
	v_add_f32_e32 v12, v12, v56
	v_add_f32_e32 v13, v13, v56
	v_add_f32_e32 v14, v14, v56
	v_add_f32_e32 v15, v15, v56
	v_add_f32_e32 v16, v16, v56
	v_add_f32_e32 v17, v17, v56
	v_sub_u32_e32 v2, v98, v2
	s_add_i32 s2, 0, 0x10c80
	v_exp_f32_e32 v199, v18
	v_exp_f32_e32 v201, v19
	v_exp_f32_e32 v202, v20
	v_exp_f32_e32 v205, v21
	v_exp_f32_e32 v207, v22
	v_exp_f32_e32 v209, v23
	v_exp_f32_e32 v211, v24
	v_exp_f32_e32 v213, v25
	v_exp_f32_e32 v215, v26
	v_exp_f32_e32 v216, v27
	v_exp_f32_e32 v217, v28
	v_exp_f32_e32 v218, v29
	v_exp_f32_e32 v221, v30
	v_exp_f32_e32 v222, v31
	v_exp_f32_e32 v223, v32
	v_exp_f32_e32 v224, v33
	v_exp_f32_e32 v198, v5
	v_exp_f32_e32 v200, v6
	v_exp_f32_e32 v203, v7
	v_exp_f32_e32 v204, v8
	v_exp_f32_e32 v206, v9
	v_exp_f32_e32 v208, v10
	v_exp_f32_e32 v210, v11
	v_exp_f32_e32 v212, v12
	v_exp_f32_e32 v214, v13
	v_exp_f32_e32 v150, v14
	v_exp_f32_e32 v151, v15
	v_exp_f32_e32 v152, v16
	v_exp_f32_e32 v153, v17
	v_add_u32_e32 v194, s2, v2
	v_lshl_add_u64 v[2:3], s[30:31], 0, v[50:51]
	s_waitcnt vmcnt(0)
	v_mad_u64_u32 v[4:5], s[2:3], v2, s49, 0
	v_and_b32_e32 v2, 15, v52
	v_mad_i32_i24 v3, v3, s49, v5
	v_lshl_or_b32 v2, v2, 4, v4
	s_mov_b32 s82, 0
	s_waitcnt vmcnt(3)
	ds_write_b128 v183, v[34:37] offset:16384
	s_waitcnt vmcnt(2)
	ds_write_b128 v184, v[38:41] offset:16384
	s_waitcnt vmcnt(1)
	ds_write_b128 v181, v[42:45] offset:49152
	s_waitcnt vmcnt(0)
	ds_write_b128 v182, v[46:49] offset:49152
	v_mov_b32_e32 v181, v180
	s_mov_b32 s54, 0
	s_movk_i32 s55, 0x4000
	s_mov_b32 s56, 0x12000
	v_sub_u32_e32 v193, s81, v54
	s_mov_b32 s83, 2
	v_lshl_add_u64 v[160:161], s[40:41], 0, v[2:3]
	s_and_b32 s100, s42, 0x80
	v_lshrrev_b32_e32 v2, 3, v52
	v_sub_u32_e32 v3, v2, v50
	v_mul_u32_u24_e32 v3, 0x2800, v3
	v_and_b32_e32 v4, 8, v52
	v_lshlrev_b32_e32 v4, 4, v4
	v_sub_u32_e32 v3, v3, v4
	v_add_u32_e32 v3, s100, v3
	v_add_co_u32_e32 v252, vcc, v160, v3
	s_nop 1
	v_addc_co_u32_e32 v253, vcc, 0, v161, vcc
	v_add_co_u32_e32 v254, vcc, 0xa0000, v252
	s_nop 1
	v_addc_co_u32_e32 v255, vcc, 0, v253, vcc
	v_and_b32_e32 v3, 7, v52
	v_and_b32_e32 v4, 7, v2
	v_xor_b32_e32 v3, v3, v4
	v_lshlrev_b32_e32 v3, 4, v3
	v_lshl_or_b32 v235, v2, 8, v3
	v_add_u32_e32 v235, s100, v235
	v_mov_b32_e32 v2, 0
	v_mov_b32_e32 v3, v176
	v_mov_b32_e32 v4, v176
	v_mov_b32_e32 v5, v176
	v_mov_b32_e32 v6, v176
	v_mov_b32_e32 v7, v176
	v_mov_b32_e32 v8, v176
	v_mov_b32_e32 v9, v176
	v_mov_b32_e32 v10, v176
	v_mov_b32_e32 v11, v176
	v_mov_b32_e32 v12, v176
	v_mov_b32_e32 v13, v176
	v_mov_b32_e32 v14, v176
	v_mov_b32_e32 v15, v176
	v_mov_b32_e32 v16, v176
	v_mov_b32_e32 v17, v176
	v_mov_b32_e32 v18, 0
	v_mov_b32_e32 v19, v176
	v_mov_b32_e32 v20, v176
	v_mov_b32_e32 v21, v176
	v_mov_b32_e32 v22, v176
	v_mov_b32_e32 v23, v176
	v_mov_b32_e32 v24, v176
	v_mov_b32_e32 v25, v176
	v_mov_b32_e32 v26, v176
	v_mov_b32_e32 v27, v176
	v_mov_b32_e32 v28, v176
	v_mov_b32_e32 v29, v176
	v_mov_b32_e32 v30, v176
	v_mov_b32_e32 v31, v176
	v_mov_b32_e32 v32, v176
	v_mov_b32_e32 v33, v176
	v_mov_b32_e32 v34, 0
	v_mov_b32_e32 v35, v176
	v_mov_b32_e32 v36, v176
	v_mov_b32_e32 v37, v176
	v_mov_b32_e32 v38, v176
	v_mov_b32_e32 v39, v176
	v_mov_b32_e32 v40, v176
	v_mov_b32_e32 v41, v176
	v_mov_b32_e32 v42, v176
	v_mov_b32_e32 v43, v176
	v_mov_b32_e32 v44, v176
	v_mov_b32_e32 v45, v176
	v_mov_b32_e32 v46, v176
	v_mov_b32_e32 v47, v176
	v_mov_b32_e32 v48, v176
	v_mov_b32_e32 v49, v176
	v_mov_b32_e32 v50, 0
	v_mov_b32_e32 v51, v176
	v_mov_b32_e32 v52, v176
	v_mov_b32_e32 v53, v176
	v_mov_b32_e32 v54, v176
	v_mov_b32_e32 v55, v176
	v_mov_b32_e32 v56, v176
	v_mov_b32_e32 v57, v176
	v_mov_b32_e32 v58, v176
	v_mov_b32_e32 v59, v176
	v_mov_b32_e32 v60, v176
	v_mov_b32_e32 v61, v176
	v_mov_b32_e32 v62, v176
	v_mov_b32_e32 v63, v176
	v_mov_b32_e32 v64, v176
	v_mov_b32_e32 v65, v176
	s_waitcnt lgkmcnt(0)
	s_barrier
	s_branch .LBB0_346
.LBB0_345:
	s_or_b64 exec, exec, s[2:3]
	v_add_u32_e32 v177, s54, v181
	v_add_f32_e32 v176, v176, v219
	ds_read_b64_tr_b16 v[196:197], v177 offset:0
	ds_read_b64_tr_b16 v[198:199], v177 offset:0x800
	ds_read_b64_tr_b16 v[200:201], v177 offset:0x1000
	ds_read_b64_tr_b16 v[202:203], v177 offset:0x1800
	ds_read_b64_tr_b16 v[206:207], v177 offset:0x2000
	ds_read_b64_tr_b16 v[208:209], v177 offset:0x2800
	ds_read_b64_tr_b16 v[210:211], v177 offset:0x3000
	ds_read_b64_tr_b16 v[212:213], v177 offset:0x3800
	s_waitcnt lgkmcnt(0)
	v_add_f32_e32 v176, v176, v98
	v_mfma_f32_32x32x16_bf16 v[50:65], v[150:153], v[196:199], v[50:65]
	v_exp_f32_e32 v195, v66
	v_exp_f32_e32 v196, v67
	ds_read_b64_tr_b16 v[66:67], v177 offset:0x200
	v_exp_f32_e32 v197, v68
	v_exp_f32_e32 v198, v69
	ds_read_b64_tr_b16 v[68:69], v177 offset:0xa00
	v_exp_f32_e32 v199, v82
	v_mfma_f32_32x32x16_bf16 v[50:65], v[134:137], v[200:203], v[50:65]
	v_exp_f32_e32 v201, v83
	ds_read_b64_tr_b16 v[82:83], v177 offset:0x1200
	v_exp_f32_e32 v202, v84
	v_exp_f32_e32 v205, v85
	ds_read_b64_tr_b16 v[84:85], v177 offset:0x1a00
	ds_read_b64_tr_b16 v[214:215], v177 offset:0x2200
	ds_read_b64_tr_b16 v[216:217], v177 offset:0x2a00
	v_mfma_f32_32x32x16_bf16 v[50:65], v[130:133], v[206:209], v[50:65]
	ds_read_b64_tr_b16 v[218:219], v177 offset:0x3200
	ds_read_b64_tr_b16 v[220:221], v177 offset:0x3a00
	s_waitcnt lgkmcnt(0)
	v_mfma_f32_32x32x16_bf16 v[50:65], v[126:129], v[210:213], v[50:65]
	v_mfma_f32_32x32x16_bf16 v[34:49], v[150:153], v[66:69], v[34:49]
	ds_read_b64_tr_b16 v[66:67], v177 offset:0x400
	ds_read_b64_tr_b16 v[68:69], v177 offset:0xc00
	v_exp_f32_e32 v200, v70
	v_exp_f32_e32 v203, v71
	ds_read_b64_tr_b16 v[70:71], v177 offset:0x1400
	v_exp_f32_e32 v204, v72
	v_exp_f32_e32 v206, v73
	v_mfma_f32_32x32x16_bf16 v[34:49], v[134:137], v[82:85], v[34:49]
	ds_read_b64_tr_b16 v[72:73], v177 offset:0x1c00
	ds_read_b64_tr_b16 v[82:83], v177 offset:0x2400
	ds_read_b64_tr_b16 v[84:85], v177 offset:0x2c00
	v_exp_f32_e32 v207, v86
	v_exp_f32_e32 v209, v87
	ds_read_b64_tr_b16 v[86:87], v177 offset:0x3400
	v_exp_f32_e32 v211, v88
	v_mfma_f32_32x32x16_bf16 v[34:49], v[130:133], v[214:217], v[34:49]
	v_exp_f32_e32 v213, v89
	ds_read_b64_tr_b16 v[88:89], v177 offset:0x3c00
	s_waitcnt lgkmcnt(0)
	v_mfma_f32_32x32x16_bf16 v[34:49], v[126:129], v[218:221], v[34:49]
	v_mfma_f32_32x32x16_bf16 v[18:33], v[150:153], v[66:69], v[18:33]
	ds_read_b64_tr_b16 v[66:67], v177 offset:0x600
	ds_read_b64_tr_b16 v[68:69], v177 offset:0xe00
	v_exp_f32_e32 v208, v74
	v_exp_f32_e32 v210, v75
	v_exp_f32_e32 v212, v76
	v_exp_f32_e32 v214, v77
	v_exp_f32_e32 v215, v90
	v_mfma_f32_32x32x16_bf16 v[18:33], v[134:137], v[70:73], v[18:33]
	ds_read_b64_tr_b16 v[70:71], v177 offset:0x1600
	ds_read_b64_tr_b16 v[72:73], v177 offset:0x1e00
	ds_read_b64_tr_b16 v[74:75], v177 offset:0x2600
	ds_read_b64_tr_b16 v[76:77], v177 offset:0x2e00
	v_exp_f32_e32 v216, v91
	v_exp_f32_e32 v217, v92
	v_exp_f32_e32 v218, v93
	v_mfma_f32_32x32x16_bf16 v[18:33], v[130:133], v[82:85], v[18:33]
	ds_read_b64_tr_b16 v[82:83], v177 offset:0x3600
	ds_read_b64_tr_b16 v[84:85], v177 offset:0x3e00
	s_waitcnt lgkmcnt(0)
	v_mfma_f32_32x32x16_bf16 v[18:33], v[126:129], v[86:89], v[18:33]
	v_mfma_f32_32x32x16_bf16 v[2:17], v[150:153], v[66:69], v[2:17]
	v_exp_f32_e32 v221, v94
	v_exp_f32_e32 v150, v78
	v_exp_f32_e32 v222, v95
	v_exp_f32_e32 v151, v79
	v_exp_f32_e32 v223, v96
	v_exp_f32_e32 v152, v80
	v_exp_f32_e32 v224, v97
	v_mfma_f32_32x32x16_bf16 v[2:17], v[134:137], v[70:73], v[2:17]
	v_exp_f32_e32 v153, v81
	v_add_u32_e32 v182, s56, v183
	v_add_u32_e32 v234, s56, v184
	s_add_i32 s83, s83, 2
	v_add_u32_e32 v194, 0x200, v194
	v_mfma_f32_32x32x16_bf16 v[2:17], v[130:133], v[74:77], v[2:17]
	v_lshl_add_u64 v[160:161], v[160:161], 0, s[26:27]
	v_lshl_add_u64 v[252:253], v[252:253], 0, s[26:27]
	v_lshl_add_u64 v[254:255], v[254:255], 0, s[26:27]
	s_waitcnt vmcnt(0)
	ds_write_b128 v235, v[142:145] offset:49152
	ds_write_b128 v182, v[138:141]
	ds_write_b128 v234, v[154:157]
	s_mov_b32 s80, s54
	s_mov_b32 s54, s55
	s_mov_b32 s55, s56
	s_mov_b32 s56, s80
	s_cmp_ge_u32 s83, s78
	s_waitcnt lgkmcnt(0)
	s_barrier
	v_mfma_f32_32x32x16_bf16 v[2:17], v[126:129], v[82:85], v[2:17]
	s_cbranch_scc1 .LBB0_350

.Lattn_back_a:
	ds_read_b128 v[126:129], v186 offset:49152
	ds_read_b128 v[130:133], v186 offset:57344
	v_add_f32_e32 v98, 0, v199
	v_add_f32_e32 v98, v201, v98
	v_add_f32_e32 v98, v202, v98
	v_add_f32_e32 v98, v205, v98
	v_add_f32_e32 v98, v207, v98
	v_add_f32_e32 v98, v209, v98
	s_waitcnt lgkmcnt(1)
	v_mfma_f32_32x32x16_bf16 v[82:97], v[126:129], v[118:121], v[236:251]
	v_add_f32_e32 v98, v211, v98
	v_add_f32_e32 v98, v213, v98
	v_add_f32_e32 v98, v215, v98
	ds_read_b128 v[134:137], v187 offset:49152
	ds_read_b128 v[138:141], v187 offset:57344
	ds_read_b128 v[142:145], v188 offset:49152
	ds_read_b128 v[146:149], v188 offset:57344
	ds_read_b128 v[154:157], v189 offset:49152
	ds_read_b128 v[226:229], v189 offset:57344
	v_add_f32_e32 v98, v216, v98
	v_add_f32_e32 v98, v217, v98
	v_add_f32_e32 v98, v218, v98
	s_waitcnt lgkmcnt(6)
	v_mfma_f32_32x32x16_bf16 v[66:81], v[130:133], v[118:121], v[236:251]
	v_add_f32_e32 v98, v221, v98
	v_add_f32_e32 v98, v222, v98
	v_add_f32_e32 v98, v223, v98
	v_add_f32_e32 v98, v224, v98
	v_add_f32_e32 v98, v195, v98
	v_add_f32_e32 v98, v196, v98
	v_add_f32_e32 v98, v197, v98
	s_waitcnt lgkmcnt(5)
	v_mfma_f32_32x32x16_bf16 v[82:97], v[134:137], v[114:117], v[82:97]
	v_add_f32_e32 v98, v198, v98
	v_add_f32_e32 v98, v200, v98
	v_add_f32_e32 v98, v203, v98
	v_add_f32_e32 v98, v204, v98
	v_add_f32_e32 v98, v206, v98
	v_add_f32_e32 v98, v208, v98
	v_add_f32_e32 v98, v210, v98
	s_waitcnt lgkmcnt(4)
	v_mfma_f32_32x32x16_bf16 v[66:81], v[138:141], v[114:117], v[66:81]
	v_add_f32_e32 v98, v212, v98
	v_add_f32_e32 v98, v214, v98
	v_add_f32_e32 v98, v150, v98
	v_add_f32_e32 v98, v151, v98
	v_add_f32_e32 v98, v152, v98
	v_add_f32_e32 v219, v153, v98
	s_waitcnt lgkmcnt(3)
	v_mfma_f32_32x32x16_bf16 v[82:97], v[142:145], v[110:113], v[82:97]
	v_cvt_pk_bf16_f32 v134, v199, v201
	v_cvt_pk_bf16_f32 v135, v202, v205
	v_cvt_pk_bf16_f32 v136, v207, v209
	v_cvt_pk_bf16_f32 v137, v211, v213
	v_cvt_pk_bf16_f32 v138, v215, v216
	s_waitcnt lgkmcnt(2)
	v_mfma_f32_32x32x16_bf16 v[66:81], v[146:149], v[110:113], v[66:81]
	v_cvt_pk_bf16_f32 v139, v217, v218
	v_cvt_pk_bf16_f32 v140, v221, v222
	v_cvt_pk_bf16_f32 v141, v223, v224
	v_cvt_pk_bf16_f32 v126, v195, v196
	v_cvt_pk_bf16_f32 v127, v197, v198
	v_cvt_pk_bf16_f32 v128, v200, v203
	v_cvt_pk_bf16_f32 v129, v204, v206
	s_waitcnt lgkmcnt(1)
	v_mfma_f32_32x32x16_bf16 v[82:97], v[154:157], v[106:109], v[82:97]
	v_cvt_pk_bf16_f32 v130, v208, v210
	v_cvt_pk_bf16_f32 v131, v212, v214
	v_cvt_pk_bf16_f32 v132, v150, v151
	v_cvt_pk_bf16_f32 v133, v152, v153
	s_waitcnt lgkmcnt(0)
	v_mfma_f32_32x32x16_bf16 v[66:81], v[226:229], v[106:109], v[66:81]
	v_add_co_u32_e32 v150, vcc, 0x50000, v160
	s_nop 1
	v_addc_co_u32_e32 v151, vcc, 0, v161, vcc
	global_load_dwordx4 v[142:145], v[160:161], off offset:2048
	global_load_dwordx4 v[146:149], v[252:253], off
	global_load_dwordx4 v[154:157], v[150:151], off offset:2048
	s_and_saveexec_b64 s[2:3], s[8:9]
	s_cbranch_execz .LBB0_348
	ds_read2_b32 v[196:197], v194 offset1:1
	ds_read2_b32 v[198:199], v194 offset0:16 offset1:17
	ds_read2_b32 v[200:201], v194 offset0:18 offset1:19
	ds_read2_b32 v[202:203], v194 offset0:24 offset1:25
	ds_read2_b32 v[204:205], v194 offset0:26 offset1:27
	ds_read2_b32 v[206:207], v194 offset0:2 offset1:3
	ds_read2_b32 v[208:209], v194 offset0:8 offset1:9
	ds_read2_b32 v[210:211], v194 offset0:10 offset1:11
	s_waitcnt lgkmcnt(7)
	v_pk_add_f32 v[82:83], v[82:83], v[196:197]
	s_waitcnt lgkmcnt(3)
	v_pk_add_f32 v[96:97], v[96:97], v[204:205]
	v_pk_add_f32 v[94:95], v[94:95], v[202:203]
	v_pk_add_f32 v[92:93], v[92:93], v[200:201]
	v_pk_add_f32 v[90:91], v[90:91], v[198:199]
	s_waitcnt lgkmcnt(0)
	v_pk_add_f32 v[88:89], v[88:89], v[210:211]
	v_pk_add_f32 v[86:87], v[86:87], v[208:209]
	v_pk_add_f32 v[84:85], v[84:85], v[206:207]
	ds_read2_b32 v[196:197], v194 offset0:48 offset1:49
	ds_read2_b32 v[198:199], v194 offset0:50 offset1:51
	ds_read2_b32 v[200:201], v194 offset0:56 offset1:57
	ds_read2_b32 v[202:203], v194 offset0:58 offset1:59
	ds_read2_b32 v[204:205], v194 offset0:32 offset1:33
	ds_read2_b32 v[206:207], v194 offset0:34 offset1:35
	ds_read2_b32 v[208:209], v194 offset0:40 offset1:41
	ds_read2_b32 v[210:211], v194 offset0:42 offset1:43
	s_waitcnt lgkmcnt(4)
	v_pk_add_f32 v[80:81], v[80:81], v[202:203]
	v_pk_add_f32 v[78:79], v[78:79], v[200:201]
	v_pk_add_f32 v[76:77], v[76:77], v[198:199]
	v_pk_add_f32 v[74:75], v[74:75], v[196:197]
	s_waitcnt lgkmcnt(0)
	v_pk_add_f32 v[72:73], v[72:73], v[210:211]
	v_pk_add_f32 v[70:71], v[70:71], v[208:209]
	v_pk_add_f32 v[68:69], v[68:69], v[206:207]
	v_pk_add_f32 v[66:67], v[66:67], v[204:205]
.LBB0_348:
	s_or_b64 exec, exec, s[2:3]
	v_add_u32_e32 v180, s54, v181
	ds_read_b64_tr_b16 v[196:197], v180 offset:0
	ds_read_b64_tr_b16 v[198:199], v180 offset:0x800
	ds_read_b64_tr_b16 v[200:201], v180 offset:0x1000
	ds_read_b64_tr_b16 v[202:203], v180 offset:0x1800
	ds_read_b64_tr_b16 v[204:205], v180 offset:0x2000
	ds_read_b64_tr_b16 v[206:207], v180 offset:0x2800
	ds_read_b64_tr_b16 v[208:209], v180 offset:0x3000
	ds_read_b64_tr_b16 v[210:211], v180 offset:0x3800
	s_waitcnt lgkmcnt(0)
	s_addk_i32 s82, 0x80
	v_mfma_f32_32x32x16_bf16 v[50:65], v[134:137], v[196:199], v[50:65]
	v_exp_f32_e32 v213, v66
	v_exp_f32_e32 v215, v67
	ds_read_b64_tr_b16 v[66:67], v180 offset:0x200
	v_exp_f32_e32 v217, v68
	v_exp_f32_e32 v221, v69
	ds_read_b64_tr_b16 v[68:69], v180 offset:0xa00
	v_exp_f32_e32 v212, v82
	v_mfma_f32_32x32x16_bf16 v[50:65], v[138:141], v[200:203], v[50:65]
	v_exp_f32_e32 v214, v83
	ds_read_b64_tr_b16 v[82:83], v180 offset:0x1200
	v_exp_f32_e32 v216, v84
	v_exp_f32_e32 v218, v85
	ds_read_b64_tr_b16 v[84:85], v180 offset:0x1a00
	ds_read_b64_tr_b16 v[196:197], v180 offset:0x2200
	ds_read_b64_tr_b16 v[198:199], v180 offset:0x2a00
	v_mfma_f32_32x32x16_bf16 v[50:65], v[126:129], v[204:207], v[50:65]
	ds_read_b64_tr_b16 v[200:201], v180 offset:0x3200
	ds_read_b64_tr_b16 v[202:203], v180 offset:0x3a00
	s_waitcnt lgkmcnt(0)
	v_mfma_f32_32x32x16_bf16 v[50:65], v[130:133], v[208:211], v[50:65]
	v_mfma_f32_32x32x16_bf16 v[34:49], v[134:137], v[66:69], v[34:49]
	ds_read_b64_tr_b16 v[66:67], v180 offset:0x400
	ds_read_b64_tr_b16 v[68:69], v180 offset:0xc00
	v_exp_f32_e32 v205, v70
	v_exp_f32_e32 v207, v71
	ds_read_b64_tr_b16 v[70:71], v180 offset:0x1400
	v_exp_f32_e32 v209, v72
	v_exp_f32_e32 v211, v73
	v_mfma_f32_32x32x16_bf16 v[34:49], v[138:141], v[82:85], v[34:49]
	ds_read_b64_tr_b16 v[72:73], v180 offset:0x1c00
	ds_read_b64_tr_b16 v[82:83], v180 offset:0x2400
	ds_read_b64_tr_b16 v[84:85], v180 offset:0x2c00
	v_exp_f32_e32 v204, v86
	v_exp_f32_e32 v206, v87
	ds_read_b64_tr_b16 v[86:87], v180 offset:0x3400
	v_exp_f32_e32 v208, v88
	v_mfma_f32_32x32x16_bf16 v[34:49], v[126:129], v[196:199], v[34:49]
	v_exp_f32_e32 v210, v89
	ds_read_b64_tr_b16 v[88:89], v180 offset:0x3c00
	s_waitcnt lgkmcnt(0)
	v_mfma_f32_32x32x16_bf16 v[34:49], v[130:133], v[200:203], v[34:49]
	v_mfma_f32_32x32x16_bf16 v[18:33], v[134:137], v[66:69], v[18:33]
	ds_read_b64_tr_b16 v[66:67], v180 offset:0x600
	ds_read_b64_tr_b16 v[68:69], v180 offset:0xe00
	v_exp_f32_e32 v197, v74
	v_exp_f32_e32 v199, v75
	v_exp_f32_e32 v201, v76
	v_exp_f32_e32 v203, v77
	v_exp_f32_e32 v196, v90
	v_mfma_f32_32x32x16_bf16 v[18:33], v[138:141], v[70:73], v[18:33]
	ds_read_b64_tr_b16 v[70:71], v180 offset:0x1600
	ds_read_b64_tr_b16 v[72:73], v180 offset:0x1e00
	ds_read_b64_tr_b16 v[74:75], v180 offset:0x2600
	ds_read_b64_tr_b16 v[76:77], v180 offset:0x2e00
	v_exp_f32_e32 v198, v91
	v_exp_f32_e32 v200, v92
	v_exp_f32_e32 v202, v93
	v_mfma_f32_32x32x16_bf16 v[18:33], v[126:129], v[82:85], v[18:33]
	ds_read_b64_tr_b16 v[82:83], v180 offset:0x3600
	ds_read_b64_tr_b16 v[84:85], v180 offset:0x3e00
	s_waitcnt lgkmcnt(0)
	v_mfma_f32_32x32x16_bf16 v[18:33], v[130:133], v[86:89], v[18:33]
	v_mfma_f32_32x32x16_bf16 v[2:17], v[134:137], v[66:69], v[2:17]
	v_add_u32_e32 v182, s56, v183
	v_add_u32_e32 v234, s56, v184
	v_exp_f32_e32 v222, v94
	v_exp_f32_e32 v223, v78
	v_exp_f32_e32 v224, v95
	v_mfma_f32_32x32x16_bf16 v[2:17], v[138:141], v[70:73], v[2:17]
	v_exp_f32_e32 v226, v79
	v_exp_f32_e32 v227, v96
	v_exp_f32_e32 v228, v80
	v_exp_f32_e32 v229, v97
	v_exp_f32_e32 v230, v81
	s_waitcnt vmcnt(0)
	ds_write_b128 v235, v[146:149] offset:32768
	ds_write_b128 v182, v[142:145]
	ds_write_b128 v234, v[154:157]
	s_waitcnt lgkmcnt(0)
	v_mfma_f32_32x32x16_bf16 v[2:17], v[126:129], v[74:77], v[2:17]
	s_barrier
	v_mfma_f32_32x32x16_bf16 v[2:17], v[130:133], v[82:85], v[2:17]
	s_mov_b32 s80, s54
	s_mov_b32 s54, s55
	s_mov_b32 s55, s56
	s_mov_b32 s56, s80
	s_cmp_eq_u32 s82, s99
	s_cbranch_scc1 .Lattn_refill_b
.Lattn_back_b:
	ds_read_b128 v[126:129], v186 offset:32768
	ds_read_b128 v[130:133], v186 offset:40960
	ds_read_b128 v[134:137], v187 offset:32768
	ds_read_b128 v[138:141], v187 offset:40960
	v_add_f32_e32 v98, 0, v212
	v_add_f32_e32 v98, v214, v98
	v_add_f32_e32 v98, v216, v98
	v_add_f32_e32 v98, v218, v98
	v_add_f32_e32 v98, v204, v98
	v_add_f32_e32 v98, v206, v98
	v_add_f32_e32 v98, v208, v98
	s_waitcnt lgkmcnt(3)
	v_mfma_f32_32x32x16_bf16 v[82:97], v[126:129], v[118:121], v[236:251]
	v_add_f32_e32 v98, v210, v98
	v_add_f32_e32 v98, v196, v98
	v_add_f32_e32 v98, v198, v98
	v_add_f32_e32 v98, v200, v98
	v_add_f32_e32 v98, v202, v98
	v_add_f32_e32 v98, v222, v98
	v_add_f32_e32 v98, v224, v98
	s_waitcnt lgkmcnt(2)
	v_mfma_f32_32x32x16_bf16 v[66:81], v[130:133], v[118:121], v[236:251]
	v_add_f32_e32 v98, v227, v98
	ds_read_b128 v[126:129], v188 offset:32768
	ds_read_b128 v[142:145], v188 offset:40960
	ds_read_b128 v[146:149], v189 offset:32768
	ds_read_b128 v[154:157], v189 offset:40960
	v_add_f32_e32 v98, v229, v98
	v_add_f32_e32 v98, v213, v98
	v_add_f32_e32 v98, v215, v98
	v_add_f32_e32 v98, v217, v98
	v_add_f32_e32 v98, v221, v98
	s_waitcnt lgkmcnt(5)
	v_mfma_f32_32x32x16_bf16 v[82:97], v[134:137], v[114:117], v[82:97]
	v_add_f32_e32 v98, v205, v98
	v_add_f32_e32 v98, v207, v98
	v_add_f32_e32 v98, v209, v98
	v_add_f32_e32 v98, v211, v98
	v_add_f32_e32 v98, v197, v98
	v_add_f32_e32 v98, v199, v98
	v_add_f32_e32 v98, v201, v98
	s_waitcnt lgkmcnt(4)
	v_mfma_f32_32x32x16_bf16 v[66:81], v[138:141], v[114:117], v[66:81]
	v_add_f32_e32 v98, v203, v98
	v_add_f32_e32 v98, v223, v98
	v_add_f32_e32 v98, v226, v98
	v_add_f32_e32 v98, v228, v98
	v_add_f32_e32 v98, v230, v98
	s_waitcnt lgkmcnt(3)
	v_mfma_f32_32x32x16_bf16 v[82:97], v[126:129], v[110:113], v[82:97]
	v_cvt_pk_bf16_f32 v150, v212, v214
	v_cvt_pk_bf16_f32 v151, v216, v218
	v_cvt_pk_bf16_f32 v152, v204, v206
	v_cvt_pk_bf16_f32 v153, v208, v210
	v_cvt_pk_bf16_f32 v134, v196, v198
	v_cvt_pk_bf16_f32 v135, v200, v202
	v_cvt_pk_bf16_f32 v136, v222, v224
	s_waitcnt lgkmcnt(2)
	v_mfma_f32_32x32x16_bf16 v[66:81], v[142:145], v[110:113], v[66:81]
	v_cvt_pk_bf16_f32 v137, v227, v229
	v_cvt_pk_bf16_f32 v130, v213, v215
	v_cvt_pk_bf16_f32 v131, v217, v221
	v_cvt_pk_bf16_f32 v132, v205, v207
	v_cvt_pk_bf16_f32 v133, v209, v211
	v_cvt_pk_bf16_f32 v126, v197, v199
	v_cvt_pk_bf16_f32 v127, v201, v203
	s_waitcnt lgkmcnt(1)
	v_mfma_f32_32x32x16_bf16 v[82:97], v[146:149], v[106:109], v[82:97]
	v_cvt_pk_bf16_f32 v128, v223, v226
	v_cvt_pk_bf16_f32 v129, v228, v230
	s_waitcnt lgkmcnt(0)
	v_mfma_f32_32x32x16_bf16 v[66:81], v[154:157], v[106:109], v[66:81]
	v_add_co_u32_e32 v142, vcc, 0xa0000, v160
	s_nop 1
	v_addc_co_u32_e32 v143, vcc, 0, v161, vcc
	v_add_co_u32_e32 v146, vcc, 0xf0000, v160
	s_nop 1
	v_addc_co_u32_e32 v147, vcc, 0, v161, vcc
	global_load_dwordx4 v[138:141], v[142:143], off offset:2048
	s_nop 0
	global_load_dwordx4 v[142:145], v[254:255], off
	s_nop 0
	global_load_dwordx4 v[154:157], v[146:147], off offset:2048
	s_and_saveexec_b64 s[2:3], s[8:9]
	s_cbranch_execz .LBB0_345
	ds_read2_b32 v[196:197], v194 offset0:64 offset1:65
	ds_read2_b32 v[198:199], v194 offset0:80 offset1:81
	ds_read2_b32 v[200:201], v194 offset0:82 offset1:83
	ds_read2_b32 v[202:203], v194 offset0:88 offset1:89
	ds_read2_b32 v[204:205], v194 offset0:90 offset1:91
	ds_read2_b32 v[206:207], v194 offset0:66 offset1:67
	ds_read2_b32 v[208:209], v194 offset0:72 offset1:73
	ds_read2_b32 v[210:211], v194 offset0:74 offset1:75
	s_waitcnt lgkmcnt(7)
	v_pk_add_f32 v[82:83], v[82:83], v[196:197]
	s_waitcnt lgkmcnt(3)
	v_pk_add_f32 v[96:97], v[96:97], v[204:205]
	v_pk_add_f32 v[94:95], v[94:95], v[202:203]
	v_pk_add_f32 v[92:93], v[92:93], v[200:201]
	v_pk_add_f32 v[90:91], v[90:91], v[198:199]
	s_waitcnt lgkmcnt(0)
	v_pk_add_f32 v[88:89], v[88:89], v[210:211]
	v_pk_add_f32 v[86:87], v[86:87], v[208:209]
	v_pk_add_f32 v[84:85], v[84:85], v[206:207]
	ds_read2_b32 v[196:197], v194 offset0:112 offset1:113
	ds_read2_b32 v[198:199], v194 offset0:114 offset1:115
	ds_read2_b32 v[200:201], v194 offset0:120 offset1:121
	ds_read2_b32 v[202:203], v194 offset0:122 offset1:123
	ds_read2_b32 v[204:205], v194 offset0:96 offset1:97
	ds_read2_b32 v[206:207], v194 offset0:98 offset1:99
	ds_read2_b32 v[208:209], v194 offset0:104 offset1:105
	ds_read2_b32 v[210:211], v194 offset0:106 offset1:107
	s_waitcnt lgkmcnt(4)
	v_pk_add_f32 v[80:81], v[80:81], v[202:203]
	v_pk_add_f32 v[78:79], v[78:79], v[200:201]
	v_pk_add_f32 v[76:77], v[76:77], v[198:199]
	v_pk_add_f32 v[74:75], v[74:75], v[196:197]
	s_waitcnt lgkmcnt(0)
	v_pk_add_f32 v[72:73], v[72:73], v[210:211]
	v_pk_add_f32 v[70:71], v[70:71], v[208:209]
	v_pk_add_f32 v[68:69], v[68:69], v[206:207]
	v_pk_add_f32 v[66:67], v[66:67], v[204:205]
	s_branch .LBB0_345

.LBB0_352:
	s_or_b64 exec, exec, s[2:3]
	v_add_u32_e32 v180, s54, v181
	ds_read_b64_tr_b16 v[124:125], v180 offset:0
	ds_read_b64_tr_b16 v[126:127], v180 offset:0x800
	ds_read_b64_tr_b16 v[128:129], v180 offset:0x1000
	ds_read_b64_tr_b16 v[130:131], v180 offset:0x1800
	ds_read_b64_tr_b16 v[132:133], v180 offset:0x2000
	ds_read_b64_tr_b16 v[134:135], v180 offset:0x2800
	ds_read_b64_tr_b16 v[136:137], v180 offset:0x3000
	ds_read_b64_tr_b16 v[138:139], v180 offset:0x3800
	s_waitcnt lgkmcnt(0)
	s_nop 0
	v_mfma_f32_32x32x16_bf16 v[50:65], v[114:117], v[124:127], v[50:65]
	s_nop 6
	v_exp_f32_e32 v140, v66
	v_exp_f32_e32 v142, v67
	ds_read_b64_tr_b16 v[66:67], v180 offset:0x200
	v_exp_f32_e32 v144, v68
	v_exp_f32_e32 v146, v69
	ds_read_b64_tr_b16 v[68:69], v180 offset:0xa00
	v_exp_f32_e32 v98, v82
	v_mfma_f32_32x32x16_bf16 v[50:65], v[110:113], v[128:131], v[50:65]
	v_exp_f32_e32 v141, v83
	ds_read_b64_tr_b16 v[82:83], v180 offset:0x1200
	v_exp_f32_e32 v143, v84
	v_exp_f32_e32 v145, v85
	ds_read_b64_tr_b16 v[84:85], v180 offset:0x1a00
	ds_read_b64_tr_b16 v[124:125], v180 offset:0x2200
	ds_read_b64_tr_b16 v[126:127], v180 offset:0x2a00
	v_mfma_f32_32x32x16_bf16 v[50:65], v[118:121], v[132:135], v[50:65]
	ds_read_b64_tr_b16 v[128:129], v180 offset:0x3200
	ds_read_b64_tr_b16 v[130:131], v180 offset:0x3a00
	s_waitcnt lgkmcnt(0)
	v_mfma_f32_32x32x16_bf16 v[50:65], v[106:109], v[136:139], v[50:65]
	v_mfma_f32_32x32x16_bf16 v[34:49], v[114:117], v[66:69], v[34:49]
	ds_read_b64_tr_b16 v[66:67], v180 offset:0x400
	ds_read_b64_tr_b16 v[68:69], v180 offset:0xc00
	v_exp_f32_e32 v133, v70
	v_exp_f32_e32 v135, v71
	ds_read_b64_tr_b16 v[70:71], v180 offset:0x1400
	v_exp_f32_e32 v137, v72
	v_exp_f32_e32 v139, v73
	v_mfma_f32_32x32x16_bf16 v[34:49], v[110:113], v[82:85], v[34:49]
	ds_read_b64_tr_b16 v[72:73], v180 offset:0x1c00
	ds_read_b64_tr_b16 v[82:83], v180 offset:0x2400
	ds_read_b64_tr_b16 v[84:85], v180 offset:0x2c00
	v_exp_f32_e32 v132, v86
	v_exp_f32_e32 v134, v87
	ds_read_b64_tr_b16 v[86:87], v180 offset:0x3400
	v_exp_f32_e32 v136, v88
	v_mfma_f32_32x32x16_bf16 v[34:49], v[118:121], v[124:127], v[34:49]
	v_exp_f32_e32 v138, v89
	ds_read_b64_tr_b16 v[88:89], v180 offset:0x3c00
	s_waitcnt lgkmcnt(0)
	v_mfma_f32_32x32x16_bf16 v[34:49], v[106:109], v[128:131], v[34:49]
	v_mfma_f32_32x32x16_bf16 v[18:33], v[114:117], v[66:69], v[18:33]
	ds_read_b64_tr_b16 v[66:67], v180 offset:0x600
	ds_read_b64_tr_b16 v[68:69], v180 offset:0xe00
	v_exp_f32_e32 v124, v74
	v_exp_f32_e32 v125, v75
	v_exp_f32_e32 v126, v76
	v_exp_f32_e32 v127, v77
	v_exp_f32_e32 v90, v90
	v_mfma_f32_32x32x16_bf16 v[18:33], v[110:113], v[70:73], v[18:33]
	ds_read_b64_tr_b16 v[70:71], v180 offset:0x1600
	ds_read_b64_tr_b16 v[72:73], v180 offset:0x1e00
	ds_read_b64_tr_b16 v[74:75], v180 offset:0x2600
	ds_read_b64_tr_b16 v[76:77], v180 offset:0x2e00
	v_exp_f32_e32 v91, v91
	v_exp_f32_e32 v92, v92
	v_exp_f32_e32 v93, v93
	v_mfma_f32_32x32x16_bf16 v[18:33], v[118:121], v[82:85], v[18:33]
	ds_read_b64_tr_b16 v[82:83], v180 offset:0x3600
	ds_read_b64_tr_b16 v[84:85], v180 offset:0x3e00
	s_waitcnt lgkmcnt(0)
	v_mfma_f32_32x32x16_bf16 v[18:33], v[106:109], v[86:89], v[18:33]
	v_mfma_f32_32x32x16_bf16 v[2:17], v[114:117], v[66:69], v[2:17]
	v_add_f32_e32 v66, 0, v98
	v_add_f32_e32 v66, v141, v66
	v_add_f32_e32 v66, v143, v66
	v_add_f32_e32 v66, v145, v66
	v_add_f32_e32 v66, v132, v66
	v_add_f32_e32 v66, v134, v66
	v_add_f32_e32 v66, v136, v66
	v_add_f32_e32 v66, v138, v66
	v_exp_f32_e32 v86, v94
	v_add_f32_e32 v66, v90, v66
	v_exp_f32_e32 v87, v78
	v_exp_f32_e32 v78, v95
	v_add_f32_e32 v66, v91, v66
	v_exp_f32_e32 v88, v79
	v_exp_f32_e32 v79, v96
	v_mfma_f32_32x32x16_bf16 v[2:17], v[110:113], v[70:73], v[2:17]
	v_add_f32_e32 v66, v92, v66
	v_exp_f32_e32 v89, v80
	v_exp_f32_e32 v80, v97
	v_add_f32_e32 v66, v93, v66
	v_add_f32_e32 v66, v86, v66
	v_add_f32_e32 v66, v78, v66
	v_add_f32_e32 v66, v79, v66
	v_add_f32_e32 v66, v80, v66
	v_add_f32_e32 v66, v140, v66
	v_add_f32_e32 v66, v142, v66
	v_mfma_f32_32x32x16_bf16 v[2:17], v[118:121], v[74:77], v[2:17]
	v_add_f32_e32 v66, v144, v66
	v_add_f32_e32 v66, v146, v66
	v_add_f32_e32 v66, v133, v66
	v_add_f32_e32 v66, v135, v66
	v_add_f32_e32 v66, v137, v66
	v_add_f32_e32 v66, v139, v66
	v_add_f32_e32 v66, v124, v66
	v_add_f32_e32 v66, v125, v66
	v_mfma_f32_32x32x16_bf16 v[2:17], v[106:109], v[82:85], v[2:17]
	v_add_f32_e32 v66, v126, v66
	v_exp_f32_e32 v81, v81
	v_add_f32_e32 v66, v127, v66
	v_add_f32_e32 v66, v87, v66
	v_add_f32_e32 v66, v88, v66
	v_add_f32_e32 v66, v89, v66
	v_add_f32_e32 v101, v81, v66
	v_mov_b32_e32 v123, v101
	s_nop 1
	v_permlane32_swap_b32_e32 v101, v123
	s_barrier
	v_cvt_pk_bf16_f32 v66, v98, v141
	v_cvt_pk_bf16_f32 v67, v143, v145
	v_cvt_pk_bf16_f32 v68, v132, v134
	v_cvt_pk_bf16_f32 v69, v136, v138
	v_cvt_pk_bf16_f32 v70, v90, v91
	v_cvt_pk_bf16_f32 v71, v92, v93
	v_cvt_pk_bf16_f32 v72, v86, v78
	v_cvt_pk_bf16_f32 v73, v79, v80
	v_cvt_pk_bf16_f32 v74, v140, v142
	v_cvt_pk_bf16_f32 v75, v144, v146
	v_cvt_pk_bf16_f32 v76, v133, v135
	v_cvt_pk_bf16_f32 v77, v137, v139
	v_cvt_pk_bf16_f32 v78, v124, v125
	v_cvt_pk_bf16_f32 v79, v126, v127
	v_cvt_pk_bf16_f32 v80, v87, v88
	v_cvt_pk_bf16_f32 v81, v89, v81
	v_add_u32_e32 v177, s55, v181
	ds_read_b64_tr_b16 v[82:83], v177 offset:0
	ds_read_b64_tr_b16 v[84:85], v177 offset:0x800
	ds_read_b64_tr_b16 v[86:87], v177 offset:0x1000
	ds_read_b64_tr_b16 v[88:89], v177 offset:0x1800
	ds_read_b64_tr_b16 v[90:91], v177 offset:0x2000
	ds_read_b64_tr_b16 v[92:93], v177 offset:0x2800
	ds_read_b64_tr_b16 v[94:95], v177 offset:0x3000
	ds_read_b64_tr_b16 v[96:97], v177 offset:0x3800
	s_waitcnt lgkmcnt(0)
	s_nop 0
	v_mfma_f32_32x32x16_bf16 v[50:65], v[66:69], v[82:85], v[50:65]
	ds_read_b64_tr_b16 v[82:83], v177 offset:0x200
	ds_read_b64_tr_b16 v[84:85], v177 offset:0xa00
	v_mfma_f32_32x32x16_bf16 v[50:65], v[70:73], v[86:89], v[50:65]
	ds_read_b64_tr_b16 v[86:87], v177 offset:0x1200
	ds_read_b64_tr_b16 v[88:89], v177 offset:0x1a00
	v_mfma_f32_32x32x16_bf16 v[50:65], v[74:77], v[90:93], v[50:65]
	ds_read_b64_tr_b16 v[90:91], v177 offset:0x2200
	ds_read_b64_tr_b16 v[92:93], v177 offset:0x2a00
	ds_read_b64_tr_b16 v[106:107], v177 offset:0x3200
	ds_read_b64_tr_b16 v[108:109], v177 offset:0x3a00
	s_waitcnt lgkmcnt(0)
	v_mfma_f32_32x32x16_bf16 v[50:65], v[78:81], v[94:97], v[50:65]
	v_mfma_f32_32x32x16_bf16 v[34:49], v[66:69], v[82:85], v[34:49]
	ds_read_b64_tr_b16 v[82:83], v177 offset:0x400
	ds_read_b64_tr_b16 v[84:85], v177 offset:0xc00
	v_mfma_f32_32x32x16_bf16 v[34:49], v[70:73], v[86:89], v[34:49]
	ds_read_b64_tr_b16 v[86:87], v177 offset:0x1400
	ds_read_b64_tr_b16 v[88:89], v177 offset:0x1c00
	v_mfma_f32_32x32x16_bf16 v[34:49], v[74:77], v[90:93], v[34:49]
	ds_read_b64_tr_b16 v[90:91], v177 offset:0x2400
	ds_read_b64_tr_b16 v[92:93], v177 offset:0x2c00
	ds_read_b64_tr_b16 v[94:95], v177 offset:0x3400
	ds_read_b64_tr_b16 v[96:97], v177 offset:0x3c00
	s_waitcnt lgkmcnt(0)
	v_mfma_f32_32x32x16_bf16 v[34:49], v[78:81], v[106:109], v[34:49]
	v_mfma_f32_32x32x16_bf16 v[18:33], v[66:69], v[82:85], v[18:33]
	ds_read_b64_tr_b16 v[82:83], v177 offset:0x600
	ds_read_b64_tr_b16 v[84:85], v177 offset:0xe00
	v_mfma_f32_32x32x16_bf16 v[18:33], v[70:73], v[86:89], v[18:33]
	ds_read_b64_tr_b16 v[86:87], v177 offset:0x1600
	ds_read_b64_tr_b16 v[88:89], v177 offset:0x1e00
	v_mfma_f32_32x32x16_bf16 v[18:33], v[74:77], v[90:93], v[18:33]
	ds_read_b64_tr_b16 v[90:91], v177 offset:0x2600
	ds_read_b64_tr_b16 v[92:93], v177 offset:0x2e00
	ds_read_b64_tr_b16 v[106:107], v177 offset:0x3600
	ds_read_b64_tr_b16 v[108:109], v177 offset:0x3e00
	s_waitcnt lgkmcnt(0)
	v_mfma_f32_32x32x16_bf16 v[18:33], v[78:81], v[94:97], v[18:33]
	v_mfma_f32_32x32x16_bf16 v[2:17], v[66:69], v[82:85], v[2:17]
	v_mov_b32_e32 v66, v163
	v_mov_b32_e32 v69, v164
	v_mfma_f32_32x32x16_bf16 v[2:17], v[70:73], v[86:89], v[2:17]
	v_mfma_f32_32x32x16_bf16 v[2:17], v[74:77], v[90:93], v[2:17]
	v_mfma_f32_32x32x16_bf16 v[2:17], v[78:81], v[106:109], v[2:17]
	s_and_saveexec_b64 s[2:3], s[4:5]
	v_pk_add_f32 v[70:71], v[100:101], v[122:123]
	s_nop 0
	v_add_f32_e32 v67, v176, v70
	v_add_f32_e32 v67, v67, v71
	ds_write_b32 v168, v67
	s_or_b64 exec, exec, s[2:3]
	s_waitcnt lgkmcnt(0)
	v_lshl_add_u32 v68, v69, 4, v165
	s_mov_b64 s[2:3], -1
	s_and_b64 vcc, exec, s[42:43]
	s_cbranch_vccnz .LBB0_356
	s_andn2_b64 vcc, exec, s[2:3]
	s_cbranch_vccnz .LBB0_335
	s_branch .LBB0_357

	.amdhsa_kernel _Z4mega6Params
		.amdhsa_group_segment_fixed_size 0
		.amdhsa_private_segment_fixed_size 0
		.amdhsa_kernarg_size 416
		.amdhsa_user_sgpr_count 2
		.amdhsa_user_sgpr_dispatch_ptr 0
		.amdhsa_user_sgpr_queue_ptr 0
		.amdhsa_user_sgpr_kernarg_segment_ptr 1
		.amdhsa_user_sgpr_dispatch_id 0
		.amdhsa_user_sgpr_kernarg_preload_length 0
		.amdhsa_user_sgpr_kernarg_preload_offset 0
		.amdhsa_user_sgpr_private_segment_size 0
		.amdhsa_uses_dynamic_stack 0
		.amdhsa_enable_private_segment 0
		.amdhsa_system_sgpr_workgroup_id_x 1
		.amdhsa_system_sgpr_workgroup_id_y 0
		.amdhsa_system_sgpr_workgroup_id_z 0
		.amdhsa_system_sgpr_workgroup_info 0
		.amdhsa_system_vgpr_workitem_id 2
		.amdhsa_next_free_vgpr 256
		.amdhsa_next_free_sgpr 102
		.amdhsa_accum_offset 256
		.amdhsa_reserve_vcc 1
		.amdhsa_float_round_mode_32 0
		.amdhsa_float_round_mode_16_64 0
		.amdhsa_float_denorm_mode_32 3
		.amdhsa_float_denorm_mode_16_64 3
		.amdhsa_dx10_clamp 1
		.amdhsa_ieee_mode 1
		.amdhsa_fp16_overflow 0
		.amdhsa_tg_split 0
		.amdhsa_exception_fp_ieee_invalid_op 0
		.amdhsa_exception_fp_denorm_src 0
		.amdhsa_exception_fp_ieee_div_zero 0
		.amdhsa_exception_fp_ieee_overflow 0
		.amdhsa_exception_fp_ieee_underflow 0
		.amdhsa_exception_fp_ieee_inexact 0
		.amdhsa_exception_int_div_zero 0
	.end_amdhsa_kernel

amdhsa.kernels:
  - .agpr_count:     0
    .args:
      - .offset:         0
        .size:           160
        .value_kind:     by_value
      - .offset:         160
        .size:           4
        .value_kind:     hidden_block_count_x
      - .offset:         164
        .size:           4
        .value_kind:     hidden_block_count_y
      - .offset:         168
        .size:           4
        .value_kind:     hidden_block_count_z
      - .offset:         172
        .size:           2
        .value_kind:     hidden_group_size_x
      - .offset:         174
        .size:           2
        .value_kind:     hidden_group_size_y
      - .offset:         176
        .size:           2
        .value_kind:     hidden_group_size_z
      - .offset:         178
        .size:           2
        .value_kind:     hidden_remainder_x
      - .offset:         180
        .size:           2
        .value_kind:     hidden_remainder_y
      - .offset:         182
        .size:           2
        .value_kind:     hidden_remainder_z
      - .offset:         200
        .size:           8
        .value_kind:     hidden_global_offset_x
      - .offset:         208
        .size:           8
        .value_kind:     hidden_global_offset_y
      - .offset:         216
        .size:           8
        .value_kind:     hidden_global_offset_z
      - .offset:         224
        .size:           2
        .value_kind:     hidden_grid_dims
      - .offset:         248
        .size:           8
        .value_kind:     hidden_multigrid_sync_arg
      - .offset:         280
        .size:           4
        .value_kind:     hidden_dynamic_lds_size
    .group_segment_fixed_size: 0
    .kernarg_segment_align: 8
    .kernarg_segment_size: 416
    .language:       OpenCL C
    .language_version:
      - 2
      - 0
    .max_flat_workgroup_size: 512
    .name:           _Z4mega6Params
    .private_segment_fixed_size: 0
    .sgpr_count:     108
    .sgpr_spill_count: 83
    .symbol:         _Z4mega6Params.kd
    .uniform_work_group_size: 1
    .uses_dynamic_stack: false
    .vgpr_count:     256
    .vgpr_spill_count: 0
    .wavefront_size: 64
